# attention unit start: Q, K0, K1, V loads in flight together (removed the serializing wait)
# speedup vs baseline: 1.0007x; 1.0007x over previous
; #define GAS __attribute__((address_space(1)))
; #define GAS __attribute__((address_space(1)))
; template <int VAR> DI void phase_attn(LAS unsigned char* lds, const bf16_t* Q, const bf16_t* K, const bf16_t* VT, bf16_t* O) {
;     ...
;         int tq = qw0 + r32; if (tq > TT - 1) tq = TT - 1;
;         bf16x8 qr[6];
;         { const bf16_t* qp = Q + (rowb + tq) * 1536 + h * 96 + 8 * hi;
; #pragma unroll
;           for (int s = 0; s < 6; ++s) qr[s] = *(GAS const bf16x8*)(qp + 16 * s); }
;         const bf16_t* Kh = K + (size_t)bh * TT * 96; const bf16_t* Vh = VT + (size_t)(bh * 64 + vd) * 4160;
;         u32x4 kr0, kr1 = {0u, 0u, 0u, 0u}, vr;
.LBB0_42:
	s_lshl_b32 s41, s8, 8
	s_add_i32 s36, s41, s17
	v_or_b32_e32 v201, s36, v134
	v_min_i32_e32 v0, 0x100f, v201
	s_ashr_i32 s37, s40, 4
	v_ashrrev_i32_e32 v1, 31, v0
	v_mov_b32_e32 v2, 0x1010
	v_mad_i64_i32 v[0:1], s[0:1], s37, v2, v[0:1]
	v_mov_b64_e32 v[2:3], s[28:29]
	s_and_b32 s19, s40, 15
	v_mad_u64_u32 v[2:3], s[0:1], v0, s84, v[2:3]
	v_mad_i32_i24 v3, v1, s84, v3
	s_mul_i32 s98, s19, 0xc0
	v_lshl_add_u64 v[0:1], v[2:3], 0, s[98:99]
	v_lshl_add_u64 v[0:1], v[0:1], 0, v[64:65]
	s_mul_i32 s1, s40, 0xc0c00
	v_mov_b32_e32 v94, v65
	v_mov_b32_e32 v95, v65
	v_mov_b32_e32 v96, v65
	v_mov_b32_e32 v97, v65
	global_load_dwordx4 v[66:69], v[0:1], off
	global_load_dwordx4 v[70:73], v[0:1], off offset:32
	global_load_dwordx4 v[74:77], v[0:1], off offset:64
	global_load_dwordx4 v[78:81], v[0:1], off offset:96
	global_load_dwordx4 v[82:85], v[0:1], off offset:128
	global_load_dwordx4 v[86:89], v[0:1], off offset:160
	s_mul_hi_i32 s0, s40, 0xc0c00
	s_add_u32 s8, s10, s1
	s_addc_u32 s9, s11, s0
	v_lshl_add_u64 v[0:1], s[8:9], 0, v[136:137]
	v_lshl_add_u64 v[0:1], v[138:139], 1, v[0:1]
	global_load_dwordx4 v[90:93], v[0:1], off
	s_and_saveexec_b64 s[0:1], s[6:7]
	s_cbranch_execz .LBB0_44
	v_lshl_add_u64 v[0:1], s[8:9], 0, v[140:141]
	v_lshl_add_u64 v[0:1], v[142:143], 1, v[0:1]
	global_load_dwordx4 v[94:97], v[0:1], off
